# prologue tail: WqN row loop loads batched; left-over transpose items rotated to waves without a WqN row; placeholder nops compressed
# speedup vs baseline: 1.0072x; 1.0021x over previous
; __device__ __forceinline__ unsigned cvt_pk_bf16(float lo, float hi) { const f32x2cv v = {lo, hi}; const bf16x2cv b = __builtin_convertvector(v, bf16x2cv); return __builtin_bit_cast(unsigned, b); }
; #define LAS __attribute__((address_space(3)))
; __device__ __forceinline__ void transpose_item(const float* W, int K, int N, bf16* WT, int rs, int off, const float* sc, LAS float* scr, int item, int nblk, int lane, int swp) {
;     ...
;     for (int j = 0; j < 4; ++j) { const int nn = (lane >> 3) + 8 * j; const LAS float* s = scr + (8 * c) * 33 + nn;
;         v4u o; o.x = cvt_pk_bf16(s[0 * 33] * s0[0], s[1 * 33] * s0[1]); o.y = cvt_pk_bf16(s[2 * 33] * s0[2], s[3 * 33] * s0[3]); o.z = cvt_pk_bf16(s[4 * 33] * s1[0], s[5 * 33] * s1[1]); o.w = cvt_pk_bf16(s[6 * 33] * s1[2], s[7 * 33] * s1[3]);
;         const int ng = n0 + nn, t256 = ng >> 8, ts256 = (t256 == 2) ? 7 : (t256 == 7) ? 2 : t256, dr = swp ? ts256 * 256 + (ng & 255) : (ng / 128) * rs + off + (ng % 128);
;         *(v4u*)(WT + (size_t)dr * K + k0 + 8 * c) = o; }
; __device__ __forceinline__ void prologue(Frame& F, const Args& A, int l) {
;     LAS float* scr = (LAS float*)(F.lds + F.wave * 16384);
;     const int gw = F.vcu * NWAVES + F.wave, NGW = F.G * NWAVES;
;     unsigned char* ws = F.ws;
;     const size_t oFF = (size_t)l * DM * FFH, oDD = (size_t)l * DM * DM;
;     constexpr int I_GU = 16 * 88, I_DN = 44 * 32, I_IN = 16 * 120, I_SQ = 16 * 32;
;     constexpr int NITEMS = 6 * 1408 + I_IN + 4 * I_SQ;
;     for (int it = gw; it < NITEMS; it += NGW) {
;         int r = it, si, sci = -1, K = DM, N = FFH, rs = 128, off = 0, nblk = 32; size_t so = oFF, dsto;
.LBB0_8:
	s_ashr_i32 s35, s4, 6
	s_lshl_b32 s36, s1, 3
	v_readlane_b32 s4, v255, 18
	s_add_i32 s34, s36, s35
	s_lshl_b32 s12, s0, 3
	s_lshl_b32 s4, s4, 10
	v_and_b32_e32 v20, 63, v9
	s_cmpk_gt_i32 s34, 0x307f
	v_readlane_b32 s5, v255, 19
	s_cbranch_scc1 .LBB0_49
	s_lshl_b32 s8, s35, 14
	s_mul_i32 s68, s4, 0xb00
	s_add_i32 s2, s2, s8
	v_and_b32_e32 v21, 31, v9
	v_lshrrev_b32_e32 v22, 5, v20
	v_and_b32_e32 v2, 7, v9
	v_lshrrev_b32_e32 v23, 3, v20
	s_mov_b32 s5, s69
	s_mov_b64 s[6:7], s[68:69]
	s_mul_i32 s68, s4, 0xe08
	v_lshl_add_u32 v0, v21, 2, s2
	v_mul_u32_u24_e32 v1, 0x84, v22
	v_lshlrev_b32_e32 v8, 3, v2
	v_mul_u32_u24_e32 v2, 0x420, v2
	v_lshlrev_b32_e32 v3, 2, v23
	s_lshl_b64 s[14:15], s[4:5], 10
	s_mov_b64 s[16:17], s[68:69]
	v_add3_u32 v24, s2, v2, v3
	v_or_b32_e32 v25, 8, v23
	v_or_b32_e32 v26, 16, v23
	v_or_b32_e32 v27, 24, v23
	v_add_u32_e32 v28, v0, v1
	v_lshlrev_b32_e32 v192, 1, v8
	s_lshr_b32 s13, s12, 1
	s_add_i32 s13, s34, s13
	s_cmp_ge_i32 s13, s12
	s_cbranch_scc0 .Lpro_rot_ok
	s_sub_i32 s13, s13, s12
.Lpro_rot_ok:
	s_branch .LBB0_11
.LBB0_10:
	s_waitcnt lgkmcnt(0)
	v_pk_mul_f32 v[4:5], v[4:5], v[18:19]
	v_pk_mul_f32 v[6:7], v[6:7], v[16:17]
	v_pk_mul_f32 v[0:1], v[0:1], v[14:15]
	v_cvt_pk_bf16_f32 v4, v4, v5
	v_cvt_pk_bf16_f32 v5, v6, v7
	v_cvt_pk_bf16_f32 v6, v0, v1
	v_pk_mul_f32 v[0:1], v[2:3], v[12:13]
	s_add_i32 s13, s13, s12
	v_cvt_pk_bf16_f32 v7, v0, v1
	v_mad_i64_i32 v[0:1], s[18:19], s18, v29, 0
	v_lshl_add_u64 v[0:1], v[0:1], 1, v[10:11]
	flat_store_dwordx4 v[0:1], v[4:7]
	s_waitcnt lgkmcnt(0)
	s_cmpk_gt_i32 s13, 0x307f
	s_cbranch_scc1 .LBB0_49

; __device__ __forceinline__ unsigned cvt_pk_bf16(float lo, float hi) { const f32x2cv v = {lo, hi}; const bf16x2cv b = __builtin_convertvector(v, bf16x2cv); return __builtin_bit_cast(unsigned, b); }
; __device__ __forceinline__ void prologue(Frame& F, const Args& A, int l) {
;     ...
;     for (int d = gw; d < DM; d += NGW) {
;         const float sc = A.in[12][l * DM + d]; const f32x4* src = (const f32x4*)(A.in[14] + oDD + (size_t)d * DM) + F.lane; v2u* dst = (v2u*)((bf16*)(ws + WS_WQ) + (size_t)d * DM) + F.lane;
; #pragma unroll
;         for (int j = 0; j < 4; ++j) { const f32x4 v = src[64 * j] * sc; v2u w; w.x = cvt_pk_bf16(v[0], v[1]); w.y = cvt_pk_bf16(v[2], v[3]); dst[64 * j] = w; }
;     }
.LBB0_51:
	global_load_dword v8, v193, s[4:5]
	global_load_dwordx4 v[4:7], v[0:1], off
	global_load_dwordx4 v[22:25], v[0:1], off offset:1024
	global_load_dwordx4 v[26:29], v[0:1], off offset:2048
	global_load_dwordx4 v[30:33], v[0:1], off offset:3072
	s_add_i32 s2, s2, s12
	s_add_u32 s4, s4, s6
	s_addc_u32 s5, s5, s7
	s_cmpk_gt_i32 s2, 0x3ff
	v_lshl_add_u64 v[0:1], v[0:1], 0, s[14:15]
	s_waitcnt vmcnt(0)
	v_pk_mul_f32 v[6:7], v[8:9], v[6:7] op_sel_hi:[0,1]
	v_pk_mul_f32 v[4:5], v[8:9], v[4:5] op_sel_hi:[0,1]
	v_cvt_pk_bf16_f32 v4, v4, v5
	v_cvt_pk_bf16_f32 v5, v6, v7
	global_store_dwordx2 v[2:3], v[4:5], off
	v_pk_mul_f32 v[24:25], v[8:9], v[24:25] op_sel_hi:[0,1]
	v_pk_mul_f32 v[22:23], v[8:9], v[22:23] op_sel_hi:[0,1]
	v_cvt_pk_bf16_f32 v22, v22, v23
	v_cvt_pk_bf16_f32 v23, v24, v25
	global_store_dwordx2 v[2:3], v[22:23], off offset:512
	v_pk_mul_f32 v[28:29], v[8:9], v[28:29] op_sel_hi:[0,1]
	v_pk_mul_f32 v[26:27], v[8:9], v[26:27] op_sel_hi:[0,1]
	v_cvt_pk_bf16_f32 v26, v26, v27
	v_cvt_pk_bf16_f32 v27, v28, v29
	global_store_dwordx2 v[2:3], v[26:27], off offset:1024
	v_pk_mul_f32 v[32:33], v[8:9], v[32:33] op_sel_hi:[0,1]
	v_pk_mul_f32 v[30:31], v[8:9], v[30:31] op_sel_hi:[0,1]
	v_cvt_pk_bf16_f32 v30, v30, v31
	v_cvt_pk_bf16_f32 v31, v32, v33
	global_store_dwordx2 v[2:3], v[30:31], off offset:1536
	s_nop 0
	v_lshl_add_u64 v[2:3], v[2:3], 0, s[16:17]
	s_cbranch_scc0 .LBB0_51
